# baseline (speedup 1.0000x reference)
; #define BX mk_bx()
; DI void gatenorm_pass(const Args& a, int G, const int tid) {
;     const int lane = tid & 63, wave = tid >> 6; const int gw = BX * NWAVES + wave, NGW = G * NWAVES;
;     const bf16_t* HIN = (const bf16_t*)(a.ws + WS_HIN); bf16_t* MIX = (bf16_t*)(a.ws + WS_MIX);
;     for (int m0 = gw; m0 < R; m0 += 4 * NGW) {
;         u32x4 yw[4][2], zw[4][2];
; #pragma unroll
;         for (int q = 0; q < 4; ++q) { const int m = m0 + q * NGW; if (m < R) {
; #pragma unroll
;             for (int g = 0; g < 2; ++g) { yw[q][g] = *((const u32x4*)(MIX + (size_t)m * LDMIX + 512 + g * 512) + lane); zw[q][g] = *((const u32x4*)(HIN + (size_t)m * LDH + C_Z + g * 512) + lane); } } }
.LBB0_93:
	s_and_b64 vcc, exec, s[4:5]
	v_writelane_b32 v255, s52, 4
	s_nop 1
	v_writelane_b32 v255, s53, 5
	s_cbranch_vccz .LBB0_110
	v_mov_b32_e32 v100, 0xbfb8aa3b
	v_ashrrev_i32_e32 v0, 6, v213
	s_mov_b32 s0, s90
	s_waitcnt vmcnt(0)
	v_lshl_add_u32 v70, s0, 3, v0
	v_cmp_gt_i32_e32 vcc, s86, v70
	s_and_saveexec_b64 s[0:1], vcc
	s_cbranch_execz .LBB0_109
	v_and_b32_e32 v0, 64, v177
	v_add_u32_e32 v0, 64, v0
	s_waitcnt lgkmcnt(0)
	v_xor_b32_e32 v1, 1, v177
	v_cmp_lt_i32_e32 vcc, v1, v0
	v_and_b32_e32 v64, 63, v213
	v_readlane_b32 s2, v254, 13
	v_cndmask_b32_e32 v1, v177, v1, vcc
	v_lshlrev_b32_e32 v65, 2, v1
	v_xor_b32_e32 v1, 2, v177
	v_cmp_lt_i32_e32 vcc, v1, v0
	v_lshlrev_b32_e32 v160, 4, v64
	v_readlane_b32 s3, v254, 14
	v_cndmask_b32_e32 v1, v177, v1, vcc
	v_lshlrev_b32_e32 v76, 2, v1
	v_xor_b32_e32 v1, 4, v177
	v_cmp_lt_i32_e32 vcc, v1, v0
	v_lshl_add_u64 v[66:67], s[2:3], 0, v[160:161]
	s_mov_b64 s[2:3], 0
	v_cndmask_b32_e32 v1, v177, v1, vcc
	v_lshlrev_b32_e32 v77, 2, v1
	v_xor_b32_e32 v1, 8, v177
	v_cmp_lt_i32_e32 vcc, v1, v0
	s_nop 1
	v_cndmask_b32_e32 v1, v177, v1, vcc
	v_lshlrev_b32_e32 v78, 2, v1
	v_xor_b32_e32 v1, 16, v177
	v_cmp_lt_i32_e32 vcc, v1, v0
	s_nop 1
	v_cndmask_b32_e32 v1, v177, v1, vcc
	v_lshlrev_b32_e32 v79, 2, v1
	v_xor_b32_e32 v1, 32, v177
	v_cmp_lt_i32_e32 vcc, v1, v0
	s_nop 1
	v_cndmask_b32_e32 v0, v177, v1, vcc
	v_lshlrev_b32_e32 v80, 2, v0
	s_branch .LBB0_97

; DI float lo16(unsigned w) { return __uint_as_float(w << 16); }
; DI float hi16(unsigned w) { return __uint_as_float(w & 0xffff0000u); }
; DI void gatenorm_pass(const Args& a, int G, const int tid) {
;     ...
;         for (int q = 0; q < 4; ++q) { const int m = m0 + q * NGW; if (m < R) {
; #pragma unroll
;             for (int g = 0; g < 2; ++g) {
;                 float v[8]; float s = 0.f;
; #pragma unroll
;                 for (int e = 0; e < 4; ++e) { const float z0 = lo16(zw[q][g][e]), z1 = hi16(zw[q][g][e]); v[2 * e] = lo16(yw[q][g][e]) * z0 * __frcp_rn(1.0f + __expf(-z0)); v[2 * e + 1] = hi16(yw[q][g][e]) * z1 * __frcp_rn(1.0f + __expf(-z1)); s += v[2 * e] * v[2 * e] + v[2 * e + 1] * v[2 * e + 1]; }
;                 s = wave_sum(s); const float r = rsqrtf(s * (1.0f / 512.0f) + EPS);
.LBB0_103:
	s_or_b64 exec, exec, s[4:5]
	s_waitcnt vmcnt(1)
	v_lshlrev_b32_e32 v70, 16, v63
	v_and_b32_e32 v71, 0xffff0000, v63
	v_mul_f32_e32 v63, 0xbfb8aa3b, v70
	v_lshlrev_b32_e32 v74, 16, v59
	v_and_b32_e32 v75, 0xffff0000, v59
	v_mul_f32_e32 v59, 0xbfb8aa3b, v71
	v_exp_f32_e32 v72, v63
	v_exp_f32_e32 v73, v59
	v_pk_mul_f32 v[74:75], v[74:75], v[70:71]
	v_and_b32_e32 v85, 0xffff0000, v57
	v_and_b32_e32 v87, 0xffff0000, v51
	v_pk_add_f32 v[70:71], v[72:73], 1.0 op_sel_hi:[1,0]
	v_and_b32_e32 v89, 0xffff0000, v49
	v_rcp_f32_e32 v71, v71
	v_lshlrev_b32_e32 v72, 16, v62
	v_and_b32_e32 v73, 0xffff0000, v62
	v_rcp_f32_e32 v70, v70
	v_mul_f32_e32 v59, 0xbfb8aa3b, v72
	v_mul_f32_e32 v63, 0xbfb8aa3b, v73
	v_exp_f32_e32 v62, v59
	v_exp_f32_e32 v63, v63
	v_pk_mul_f32 v[70:71], v[74:75], v[70:71]
	v_lshlrev_b32_e32 v74, 16, v58
	v_and_b32_e32 v75, 0xffff0000, v58
	v_pk_add_f32 v[62:63], v[62:63], 1.0 op_sel_hi:[1,0]
	v_pk_mul_f32 v[58:59], v[74:75], v[72:73]
	v_rcp_f32_e32 v63, v63
	v_rcp_f32_e32 v62, v62
	s_nop 0
	v_pk_mul_f32 v[58:59], v[58:59], v[62:63]
	v_mov_b32_e32 v62, v70
	v_mov_b32_e32 v63, v58
	v_pk_mul_f32 v[62:63], v[62:63], v[62:63]
	v_mov_b32_e32 v72, v71
	v_mov_b32_e32 v73, v59
	v_pk_fma_f32 v[62:63], v[72:73], v[72:73], v[62:63]
	v_lshlrev_b32_e32 v72, 16, v61
	v_and_b32_e32 v73, 0xffff0000, v61
	v_mul_f32_e32 v61, 0xbfb8aa3b, v72
	v_lshlrev_b32_e32 v84, 16, v57
	v_mul_f32_e32 v57, 0xbfb8aa3b, v73
	v_exp_f32_e32 v74, v61
	v_exp_f32_e32 v75, v57
	v_pk_mul_f32 v[84:85], v[84:85], v[72:73]
	v_pk_add_f32 v[72:73], v[74:75], 1.0 op_sel_hi:[1,0]
	v_rcp_f32_e32 v73, v73
	v_lshlrev_b32_e32 v74, 16, v60
	v_and_b32_e32 v75, 0xffff0000, v60
	v_rcp_f32_e32 v72, v72
	v_mul_f32_e32 v57, 0xbfb8aa3b, v74
	v_mul_f32_e32 v61, 0xbfb8aa3b, v75
	v_exp_f32_e32 v60, v57
	v_exp_f32_e32 v61, v61
	v_pk_mul_f32 v[72:73], v[84:85], v[72:73]
	v_lshlrev_b32_e32 v84, 16, v56
	v_and_b32_e32 v85, 0xffff0000, v56
	v_pk_add_f32 v[60:61], v[60:61], 1.0 op_sel_hi:[1,0]
	v_pk_mul_f32 v[56:57], v[84:85], v[74:75]
	v_rcp_f32_e32 v61, v61
	v_rcp_f32_e32 v60, v60
	s_nop 0
	v_pk_mul_f32 v[56:57], v[56:57], v[60:61]
	v_mov_b32_e32 v61, v72
	v_mov_b32_e32 v60, v56
	v_pk_mul_f32 v[60:61], v[60:61], v[60:61]
	v_mov_b32_e32 v74, v57
	v_mov_b32_e32 v75, v73
	v_pk_fma_f32 v[60:61], v[74:75], v[74:75], v[60:61]
	s_waitcnt vmcnt(0)
	v_lshlrev_b32_e32 v74, 16, v55
	v_and_b32_e32 v75, 0xffff0000, v55
	v_mul_f32_e32 v55, 0xbfb8aa3b, v74
	v_lshlrev_b32_e32 v86, 16, v51
	v_mul_f32_e32 v51, 0xbfb8aa3b, v75
	v_exp_f32_e32 v84, v55
	v_exp_f32_e32 v85, v51
	v_pk_mul_f32 v[86:87], v[86:87], v[74:75]
	v_pk_add_f32 v[74:75], v[84:85], 1.0 op_sel_hi:[1,0]
	v_rcp_f32_e32 v75, v75
	v_lshlrev_b32_e32 v84, 16, v54
	v_and_b32_e32 v85, 0xffff0000, v54
	v_rcp_f32_e32 v74, v74
	v_mul_f32_e32 v51, 0xbfb8aa3b, v84
	v_mul_f32_e32 v55, 0xbfb8aa3b, v85
	v_exp_f32_e32 v54, v51
	v_exp_f32_e32 v55, v55
	v_pk_mul_f32 v[74:75], v[86:87], v[74:75]
	v_lshlrev_b32_e32 v86, 16, v50
	v_and_b32_e32 v87, 0xffff0000, v50
	v_pk_add_f32 v[54:55], v[54:55], 1.0 op_sel_hi:[1,0]
	v_pk_mul_f32 v[50:51], v[86:87], v[84:85]
	v_rcp_f32_e32 v55, v55
	v_rcp_f32_e32 v54, v54
	s_nop 0
	v_pk_mul_f32 v[50:51], v[50:51], v[54:55]
	v_mov_b32_e32 v54, v74
	v_mov_b32_e32 v55, v50
	v_pk_mul_f32 v[54:55], v[54:55], v[54:55]
	v_mov_b32_e32 v84, v75
	v_mov_b32_e32 v85, v51
	v_pk_fma_f32 v[54:55], v[84:85], v[84:85], v[54:55]
	v_lshlrev_b32_e32 v84, 16, v53
	v_and_b32_e32 v85, 0xffff0000, v53
	v_mul_f32_e32 v53, 0xbfb8aa3b, v84
	v_lshlrev_b32_e32 v88, 16, v49
	v_mul_f32_e32 v49, 0xbfb8aa3b, v85
	v_exp_f32_e32 v86, v53
	v_exp_f32_e32 v87, v49
	v_pk_mul_f32 v[88:89], v[88:89], v[84:85]
	v_pk_add_f32 v[84:85], v[86:87], 1.0 op_sel_hi:[1,0]
	v_rcp_f32_e32 v85, v85
	v_lshlrev_b32_e32 v86, 16, v52
	v_and_b32_e32 v87, 0xffff0000, v52
	v_rcp_f32_e32 v84, v84
	v_mul_f32_e32 v49, 0xbfb8aa3b, v86
	v_mul_f32_e32 v53, 0xbfb8aa3b, v87
	v_exp_f32_e32 v52, v49
	v_exp_f32_e32 v53, v53
	v_pk_mul_f32 v[84:85], v[88:89], v[84:85]
	v_lshlrev_b32_e32 v88, 16, v48
	v_and_b32_e32 v89, 0xffff0000, v48
	v_pk_add_f32 v[52:53], v[52:53], 1.0 op_sel_hi:[1,0]
	v_pk_mul_f32 v[48:49], v[88:89], v[86:87]
	v_rcp_f32_e32 v53, v53
	v_div_scale_f32 v86, s[4:5], v52, v52, 1.0
	v_rcp_f32_e32 v87, v86
	s_mov_b32 s4, 0x3b000000
	v_fma_f32 v88, -v86, v87, 1.0
	v_fmac_f32_e32 v87, v88, v87
	v_div_scale_f32 v88, vcc, 1.0, v52, 1.0
	v_mul_f32_e32 v89, v88, v87
	v_fma_f32 v90, -v86, v89, v88
	v_fmac_f32_e32 v89, v90, v87
	v_fma_f32 v86, -v86, v89, v88
	v_div_fmas_f32 v86, v86, v87, v89
	v_div_fixup_f32 v52, v86, v52, 1.0
	v_pk_mul_f32 v[48:49], v[48:49], v[52:53]
	v_mov_b32_e32 v53, v84
	v_mov_b32_e32 v52, v48
	v_pk_mul_f32 v[52:53], v[52:53], v[52:53]
	v_mov_b32_e32 v86, v49
	v_mov_b32_e32 v87, v85
	v_pk_fma_f32 v[52:53], v[86:87], v[86:87], v[52:53]
	v_mov_b32_e32 v87, v60
	v_mov_b32_e32 v86, v52
	v_mov_b32_e32 v60, v53
	v_pk_add_f32 v[52:53], v[86:87], v[60:61]
	v_mov_b32_e32 v60, v55
	v_mov_b32_e32 v61, v63
	v_pk_add_f32 v[52:53], v[60:61], v[52:53]
	v_mov_b32_e32 v55, v62
	v_pk_add_f32 v[52:53], v[54:55], v[52:53]
	ds_bpermute_b32 v55, v65, v53
	ds_bpermute_b32 v54, v65, v52
	s_waitcnt lgkmcnt(0)
	v_pk_add_f32 v[52:53], v[52:53], v[54:55]
	ds_bpermute_b32 v55, v76, v53
	ds_bpermute_b32 v54, v76, v52
	s_waitcnt lgkmcnt(0)
	v_pk_add_f32 v[52:53], v[52:53], v[54:55]
	ds_bpermute_b32 v55, v77, v53
	ds_bpermute_b32 v54, v77, v52
	s_waitcnt lgkmcnt(0)
	v_pk_add_f32 v[52:53], v[52:53], v[54:55]
	ds_bpermute_b32 v55, v78, v53
	ds_bpermute_b32 v54, v78, v52
	s_waitcnt lgkmcnt(0)
	v_pk_add_f32 v[52:53], v[52:53], v[54:55]
	ds_bpermute_b32 v55, v79, v53
	ds_bpermute_b32 v54, v79, v52
	s_waitcnt lgkmcnt(0)
; DI unsigned pk2(float lo, float hi) { const f32x2_t v = {lo, hi}; const bf16x2_t b = __builtin_convertvector(v, bf16x2_t); return __builtin_bit_cast(unsigned, b); }
; DI float lo16(unsigned w) { return __uint_as_float(w << 16); }
; DI float hi16(unsigned w) { return __uint_as_float(w & 0xffff0000u); }
; DI void gatenorm_pass(const Args& a, int G, const int tid) {
;     ...
;             for (int g = 0; g < 2; ++g) {
;                 float v[8]; float s = 0.f;
; #pragma unroll
;                 for (int e = 0; e < 4; ++e) { const float z0 = lo16(zw[q][g][e]), z1 = hi16(zw[q][g][e]); v[2 * e] = lo16(yw[q][g][e]) * z0 * __frcp_rn(1.0f + __expf(-z0)); v[2 * e + 1] = hi16(yw[q][g][e]) * z1 * __frcp_rn(1.0f + __expf(-z1)); s += v[2 * e] * v[2 * e] + v[2 * e + 1] * v[2 * e + 1]; }
;                 s = wave_sum(s); const float r = rsqrtf(s * (1.0f / 512.0f) + EPS);
;                 u32x4 w;
; #pragma unroll
;                 for (int e = 0; e < 4; ++e) w[e] = pk2(v[2 * e] * r, v[2 * e + 1] * r);
;                 *((u32x4*)(MIX + (size_t)m * LDMIX + 512 + g * 512) + lane) = w;
	v_pk_add_f32 v[52:53], v[52:53], v[54:55]
	ds_bpermute_b32 v55, v80, v53
	ds_bpermute_b32 v54, v80, v52
	s_waitcnt lgkmcnt(0)
	v_pk_add_f32 v[52:53], v[52:53], v[54:55]
	v_pk_fma_f32 v[60:61], v[52:53], s[4:5], v[176:177] op_sel_hi:[1,0,0]
	v_mul_f32_e32 v52, 0x4b800000, v61
	v_cmp_gt_f32_e64 s[46:47], s39, v61
	v_cmp_gt_f32_e32 vcc, s39, v60
	s_nop 0
	v_cndmask_b32_e64 v52, v61, v52, s[46:47]
	v_rsq_f32_e32 v52, v52
	s_nop 0
	v_mul_f32_e32 v53, 0x45800000, v52
	v_cndmask_b32_e64 v62, v52, v53, s[46:47]
	v_pk_mul_f32 v[52:53], v[56:57], v[62:63] op_sel_hi:[1,0]
	v_pk_mul_f32 v[54:55], v[72:73], v[62:63] op_sel_hi:[1,0]
	v_cvt_pk_bf16_f32 v52, v52, v53
	v_cvt_pk_bf16_f32 v53, v54, v55
	v_pk_mul_f32 v[54:55], v[58:59], v[62:63] op_sel_hi:[1,0]
	v_pk_mul_f32 v[56:57], v[70:71], v[62:63] op_sel_hi:[1,0]
	v_cvt_pk_bf16_f32 v54, v54, v55
	v_cvt_pk_bf16_f32 v55, v56, v57
	global_store_dwordx4 v[68:69], v[52:55], off offset:1024
	s_nop 1
	v_mul_f32_e32 v52, 0x4b800000, v60
	v_cndmask_b32_e32 v52, v60, v52, vcc
	v_rsq_f32_e32 v52, v52
	s_nop 0
	v_mul_f32_e32 v53, 0x45800000, v52
	v_cndmask_b32_e32 v52, v52, v53, vcc
	v_pk_mul_f32 v[48:49], v[48:49], v[52:53] op_sel_hi:[1,0]
	v_pk_mul_f32 v[54:55], v[84:85], v[52:53] op_sel_hi:[1,0]
	v_pk_mul_f32 v[50:51], v[50:51], v[52:53] op_sel_hi:[1,0]
	v_pk_mul_f32 v[52:53], v[74:75], v[52:53] op_sel_hi:[1,0]
	v_cvt_pk_bf16_f32 v48, v48, v49
	v_cvt_pk_bf16_f32 v49, v54, v55
	v_cvt_pk_bf16_f32 v50, v50, v51
	v_cvt_pk_bf16_f32 v51, v52, v53
	global_store_dwordx4 v[68:69], v[48:51], off offset:2048
	s_and_saveexec_b64 s[4:5], s[44:45]
	s_cbranch_execz .LBB0_106
	v_lshlrev_b32_e32 v48, 16, v39
	v_and_b32_e32 v49, 0xffff0000, v39
	v_pk_mul_f32 v[50:51], v[48:49], v[100:101] op_sel_hi:[1,0]
	v_exp_f32_e32 v50, v50
	v_exp_f32_e32 v51, v51
	v_lshlrev_b32_e32 v52, 16, v7
	v_and_b32_e32 v53, 0xffff0000, v7
	v_pk_mul_f32 v[48:49], v[52:53], v[48:49]
	v_pk_add_f32 v[50:51], v[50:51], 1.0 op_sel_hi:[1,0]
	v_rcp_f32_e32 v51, v51
	v_lshlrev_b32_e32 v52, 16, v38
	v_and_b32_e32 v53, 0xffff0000, v38
	v_pk_mul_f32 v[54:55], v[52:53], v[100:101] op_sel_hi:[1,0]
	v_exp_f32_e32 v54, v54
	v_exp_f32_e32 v55, v55
	v_rcp_f32_e32 v50, v50
	s_nop 0
	v_pk_mul_f32 v[48:49], v[48:49], v[50:51]
	v_pk_add_f32 v[50:51], v[54:55], 1.0 op_sel_hi:[1,0]
	v_lshlrev_b32_e32 v54, 16, v6
	v_and_b32_e32 v55, 0xffff0000, v6
	v_pk_mul_f32 v[52:53], v[54:55], v[52:53]
	v_rcp_f32_e32 v51, v51
	v_rcp_f32_e32 v50, v50
	v_lshlrev_b32_e32 v54, 16, v37
	v_and_b32_e32 v55, 0xffff0000, v37
	v_pk_mul_f32 v[56:57], v[54:55], v[100:101] op_sel_hi:[1,0]
	v_exp_f32_e32 v56, v56
	v_exp_f32_e32 v57, v57
	v_pk_mul_f32 v[50:51], v[52:53], v[50:51]
	v_mov_b32_e32 v52, v48
	v_mov_b32_e32 v53, v50
	v_pk_add_f32 v[56:57], v[56:57], 1.0 op_sel_hi:[1,0]
	v_pk_mul_f32 v[52:53], v[52:53], v[52:53]
	v_mov_b32_e32 v58, v49
	v_mov_b32_e32 v59, v51
	v_pk_fma_f32 v[52:53], v[58:59], v[58:59], v[52:53]
	v_lshlrev_b32_e32 v58, 16, v5
	v_and_b32_e32 v59, 0xffff0000, v5
	v_pk_mul_f32 v[54:55], v[58:59], v[54:55]
	v_rcp_f32_e32 v57, v57
	v_lshlrev_b32_e32 v58, 16, v36
	v_and_b32_e32 v59, 0xffff0000, v36
	v_pk_mul_f32 v[60:61], v[58:59], v[100:101] op_sel_hi:[1,0]
	v_exp_f32_e32 v60, v60
	v_exp_f32_e32 v61, v61
	v_rcp_f32_e32 v56, v56
	s_nop 0
	v_pk_mul_f32 v[54:55], v[54:55], v[56:57]
	v_pk_add_f32 v[56:57], v[60:61], 1.0 op_sel_hi:[1,0]
	v_lshlrev_b32_e32 v60, 16, v4
	v_and_b32_e32 v61, 0xffff0000, v4
	v_pk_mul_f32 v[58:59], v[60:61], v[58:59]
	v_mov_b32_e32 v69, v55
	v_rcp_f32_e32 v57, v57
	v_rcp_f32_e32 v56, v56
	v_lshlrev_b32_e32 v60, 16, v35
	v_and_b32_e32 v61, 0xffff0000, v35
	v_pk_mul_f32 v[62:63], v[60:61], v[100:101] op_sel_hi:[1,0]
	v_exp_f32_e32 v62, v62
	v_exp_f32_e32 v63, v63
	v_pk_mul_f32 v[56:57], v[58:59], v[56:57]
	v_mov_b32_e32 v59, v54
	v_mov_b32_e32 v58, v56
	v_pk_mul_f32 v[58:59], v[58:59], v[58:59]
	v_mov_b32_e32 v68, v57
	v_pk_fma_f32 v[68:69], v[68:69], v[68:69], v[58:59]
	v_pk_add_f32 v[58:59], v[62:63], 1.0 op_sel_hi:[1,0]
	v_lshlrev_b32_e32 v62, 16, v19
	v_and_b32_e32 v63, 0xffff0000, v19
	v_pk_mul_f32 v[60:61], v[62:63], v[60:61]
	v_rcp_f32_e32 v59, v59
	v_lshlrev_b32_e32 v62, 16, v34
	v_and_b32_e32 v63, 0xffff0000, v34
	v_pk_mul_f32 v[70:71], v[62:63], v[100:101] op_sel_hi:[1,0]
	v_exp_f32_e32 v70, v70
	v_exp_f32_e32 v71, v71
	v_rcp_f32_e32 v58, v58
	s_nop 0
	v_pk_mul_f32 v[58:59], v[60:61], v[58:59]
	v_pk_add_f32 v[60:61], v[70:71], 1.0 op_sel_hi:[1,0]
	v_lshlrev_b32_e32 v70, 16, v18
	v_and_b32_e32 v71, 0xffff0000, v18
	v_pk_mul_f32 v[62:63], v[70:71], v[62:63]
	v_rcp_f32_e32 v61, v61
	v_rcp_f32_e32 v60, v60
	v_lshlrev_b32_e32 v70, 16, v33
	v_and_b32_e32 v71, 0xffff0000, v33
	v_pk_mul_f32 v[72:73], v[70:71], v[100:101] op_sel_hi:[1,0]
	v_exp_f32_e32 v72, v72
	v_exp_f32_e32 v73, v73
	v_pk_mul_f32 v[60:61], v[62:63], v[60:61]
	v_mov_b32_e32 v62, v58
	v_mov_b32_e32 v63, v60
	v_pk_add_f32 v[72:73], v[72:73], 1.0 op_sel_hi:[1,0]
	v_pk_mul_f32 v[62:63], v[62:63], v[62:63]
	v_mov_b32_e32 v74, v59
	v_mov_b32_e32 v75, v61
	v_pk_fma_f32 v[62:63], v[74:75], v[74:75], v[62:63]
	v_lshlrev_b32_e32 v74, 16, v17
	v_and_b32_e32 v75, 0xffff0000, v17
	v_pk_mul_f32 v[70:71], v[74:75], v[70:71]
	v_rcp_f32_e32 v73, v73
	v_lshlrev_b32_e32 v74, 16, v32
	v_and_b32_e32 v75, 0xffff0000, v32
	v_pk_mul_f32 v[84:85], v[74:75], v[100:101] op_sel_hi:[1,0]
	v_exp_f32_e32 v84, v84
	v_exp_f32_e32 v85, v85
	v_rcp_f32_e32 v72, v72
	s_nop 0
	v_pk_mul_f32 v[70:71], v[70:71], v[72:73]
	v_pk_add_f32 v[72:73], v[84:85], 1.0 op_sel_hi:[1,0]
	v_lshlrev_b32_e32 v84, 16, v16
	v_and_b32_e32 v85, 0xffff0000, v16
	v_pk_mul_f32 v[74:75], v[84:85], v[74:75]
	v_div_scale_f32 v86, s[6:7], v72, v72, 1.0
	v_rcp_f32_e32 v88, v86
	v_rcp_f32_e32 v73, v73
	s_mov_b32 s6, 0x3b000000
	v_fma_f32 v84, -v86, v88, 1.0
	v_fmac_f32_e32 v88, v84, v88
	v_div_scale_f32 v84, vcc, 1.0, v72, 1.0
	v_mul_f32_e32 v85, v84, v88
	v_fma_f32 v87, -v86, v85, v84
	v_fmac_f32_e32 v85, v87, v88
	v_fma_f32 v84, -v86, v85, v84
	v_div_fmas_f32 v84, v84, v88, v85
	v_div_fixup_f32 v72, v84, v72, 1.0
	v_pk_mul_f32 v[72:73], v[74:75], v[72:73]
	v_mov_b32_e32 v75, v70
	v_mov_b32_e32 v74, v72
	v_pk_mul_f32 v[74:75], v[74:75], v[74:75]
	v_mov_b32_e32 v84, v73
	v_mov_b32_e32 v85, v71
	v_pk_fma_f32 v[74:75], v[84:85], v[84:85], v[74:75]
	v_mov_b32_e32 v85, v68
	v_mov_b32_e32 v84, v74
	v_mov_b32_e32 v68, v75
	v_pk_add_f32 v[68:69], v[84:85], v[68:69]
	v_mov_b32_e32 v74, v63
	v_mov_b32_e32 v75, v53
	v_pk_add_f32 v[68:69], v[74:75], v[68:69]
	v_mov_b32_e32 v63, v52
	v_pk_add_f32 v[52:53], v[62:63], v[68:69]
	ds_bpermute_b32 v63, v65, v53
	ds_bpermute_b32 v62, v65, v52
	s_waitcnt lgkmcnt(0)
; DI unsigned pk2(float lo, float hi) { const f32x2_t v = {lo, hi}; const bf16x2_t b = __builtin_convertvector(v, bf16x2_t); return __builtin_bit_cast(unsigned, b); }
; DI void gatenorm_pass(const Args& a, int G, const int tid) {
;     ...
;                 s = wave_sum(s); const float r = rsqrtf(s * (1.0f / 512.0f) + EPS);
;                 u32x4 w;
; #pragma unroll
;                 for (int e = 0; e < 4; ++e) w[e] = pk2(v[2 * e] * r, v[2 * e + 1] * r);
;                 *((u32x4*)(MIX + (size_t)m * LDMIX + 512 + g * 512) + lane) = w;
	v_pk_add_f32 v[52:53], v[52:53], v[62:63]
	ds_bpermute_b32 v63, v76, v53
	ds_bpermute_b32 v62, v76, v52
	s_waitcnt lgkmcnt(0)
	v_pk_add_f32 v[52:53], v[52:53], v[62:63]
	ds_bpermute_b32 v63, v77, v53
	ds_bpermute_b32 v62, v77, v52
	s_waitcnt lgkmcnt(0)
	v_pk_add_f32 v[52:53], v[52:53], v[62:63]
	ds_bpermute_b32 v63, v78, v53
	ds_bpermute_b32 v62, v78, v52
	s_waitcnt lgkmcnt(0)
	v_pk_add_f32 v[52:53], v[52:53], v[62:63]
	ds_bpermute_b32 v63, v79, v53
	ds_bpermute_b32 v62, v79, v52
	s_waitcnt lgkmcnt(0)
	v_pk_add_f32 v[52:53], v[52:53], v[62:63]
	ds_bpermute_b32 v63, v80, v53
	ds_bpermute_b32 v62, v80, v52
	s_waitcnt lgkmcnt(0)
	v_pk_add_f32 v[52:53], v[52:53], v[62:63]
	v_pk_fma_f32 v[62:63], v[52:53], s[6:7], v[176:177] op_sel_hi:[1,0,0]
	v_mad_i64_i32 v[68:69], s[6:7], v81, s27, v[66:67]
	v_mul_f32_e32 v52, 0x4b800000, v63
	v_cmp_gt_f32_e32 vcc, s39, v63
	s_nop 1
	v_cndmask_b32_e32 v52, v63, v52, vcc
	v_rsq_f32_e32 v52, v52
	s_nop 0
	v_mul_f32_e32 v53, 0x45800000, v52
	v_cndmask_b32_e32 v74, v52, v53, vcc
	v_pk_mul_f32 v[52:53], v[56:57], v[74:75] op_sel_hi:[1,0]
	v_pk_mul_f32 v[54:55], v[54:55], v[74:75] op_sel_hi:[1,0]
	v_pk_mul_f32 v[50:51], v[50:51], v[74:75] op_sel_hi:[1,0]
	v_cvt_pk_bf16_f32 v52, v52, v53
	v_cvt_pk_bf16_f32 v53, v54, v55
	v_cvt_pk_bf16_f32 v54, v50, v51
	v_mul_f32_e32 v50, 0x4b800000, v62
	v_cmp_gt_f32_e32 vcc, s39, v62
	v_pk_mul_f32 v[48:49], v[48:49], v[74:75] op_sel_hi:[1,0]
	s_nop 0
	v_cndmask_b32_e32 v50, v62, v50, vcc
	v_rsq_f32_e32 v50, v50
	v_cvt_pk_bf16_f32 v55, v48, v49
	global_store_dwordx4 v[68:69], v[52:55], off offset:1024
	v_mul_f32_e32 v48, 0x45800000, v50
	s_nop 0
	v_cndmask_b32_e32 v52, v50, v48, vcc
	v_pk_mul_f32 v[48:49], v[72:73], v[52:53] op_sel_hi:[1,0]
	v_pk_mul_f32 v[50:51], v[70:71], v[52:53] op_sel_hi:[1,0]
	v_cvt_pk_bf16_f32 v48, v48, v49
	v_cvt_pk_bf16_f32 v49, v50, v51
	v_pk_mul_f32 v[50:51], v[60:61], v[52:53] op_sel_hi:[1,0]
	v_pk_mul_f32 v[52:53], v[58:59], v[52:53] op_sel_hi:[1,0]
	v_cvt_pk_bf16_f32 v50, v50, v51
	v_cvt_pk_bf16_f32 v51, v52, v53
	global_store_dwordx4 v[68:69], v[48:51], off offset:2048
	s_or_b64 exec, exec, s[4:5]
	s_and_saveexec_b64 s[4:5], s[42:43]
	s_cbranch_execnz .LBB0_107

; DI float lo16(unsigned w) { return __uint_as_float(w << 16); }
; DI float hi16(unsigned w) { return __uint_as_float(w & 0xffff0000u); }
; DI void gatenorm_pass(const Args& a, int G, const int tid) {
;     ...
;             for (int g = 0; g < 2; ++g) {
;                 float v[8]; float s = 0.f;
; #pragma unroll
;                 for (int e = 0; e < 4; ++e) { const float z0 = lo16(zw[q][g][e]), z1 = hi16(zw[q][g][e]); v[2 * e] = lo16(yw[q][g][e]) * z0 * __frcp_rn(1.0f + __expf(-z0)); v[2 * e + 1] = hi16(yw[q][g][e]) * z1 * __frcp_rn(1.0f + __expf(-z1)); s += v[2 * e] * v[2 * e] + v[2 * e + 1] * v[2 * e + 1]; }
;                 s = wave_sum(s); const float r = rsqrtf(s * (1.0f / 512.0f) + EPS);
.LBB0_107:
	v_lshlrev_b32_e32 v48, 16, v47
	v_and_b32_e32 v49, 0xffff0000, v47
	v_pk_mul_f32 v[50:51], v[48:49], v[100:101] op_sel_hi:[1,0]
	v_exp_f32_e32 v50, v50
	v_exp_f32_e32 v51, v51
	v_lshlrev_b32_e32 v52, 16, v11
	v_and_b32_e32 v53, 0xffff0000, v11
	v_pk_mul_f32 v[48:49], v[52:53], v[48:49]
	v_pk_add_f32 v[50:51], v[50:51], 1.0 op_sel_hi:[1,0]
	v_rcp_f32_e32 v51, v51
	v_lshlrev_b32_e32 v52, 16, v46
	v_and_b32_e32 v53, 0xffff0000, v46
	v_pk_mul_f32 v[54:55], v[52:53], v[100:101] op_sel_hi:[1,0]
	v_exp_f32_e32 v54, v54
	v_exp_f32_e32 v55, v55
	v_rcp_f32_e32 v50, v50
	s_nop 0
	v_pk_mul_f32 v[48:49], v[48:49], v[50:51]
	v_pk_add_f32 v[50:51], v[54:55], 1.0 op_sel_hi:[1,0]
	v_lshlrev_b32_e32 v54, 16, v10
	v_and_b32_e32 v55, 0xffff0000, v10
	v_pk_mul_f32 v[52:53], v[54:55], v[52:53]
	v_rcp_f32_e32 v51, v51
	v_rcp_f32_e32 v50, v50
	v_lshlrev_b32_e32 v54, 16, v45
	v_and_b32_e32 v55, 0xffff0000, v45
	v_pk_mul_f32 v[56:57], v[54:55], v[100:101] op_sel_hi:[1,0]
	v_exp_f32_e32 v56, v56
	v_exp_f32_e32 v57, v57
	v_pk_mul_f32 v[50:51], v[52:53], v[50:51]
	v_mov_b32_e32 v52, v48
	v_mov_b32_e32 v53, v50
	v_pk_add_f32 v[56:57], v[56:57], 1.0 op_sel_hi:[1,0]
	v_pk_mul_f32 v[52:53], v[52:53], v[52:53]
	v_mov_b32_e32 v58, v49
	v_mov_b32_e32 v59, v51
	v_pk_fma_f32 v[52:53], v[58:59], v[58:59], v[52:53]
	v_lshlrev_b32_e32 v58, 16, v9
	v_and_b32_e32 v59, 0xffff0000, v9
	v_pk_mul_f32 v[54:55], v[58:59], v[54:55]
	v_rcp_f32_e32 v57, v57
	v_lshlrev_b32_e32 v58, 16, v44
	v_and_b32_e32 v59, 0xffff0000, v44
	v_pk_mul_f32 v[60:61], v[58:59], v[100:101] op_sel_hi:[1,0]
	v_exp_f32_e32 v60, v60
	v_exp_f32_e32 v61, v61
	v_rcp_f32_e32 v56, v56
	s_nop 0
	v_pk_mul_f32 v[54:55], v[54:55], v[56:57]
	v_pk_add_f32 v[56:57], v[60:61], 1.0 op_sel_hi:[1,0]
	v_lshlrev_b32_e32 v60, 16, v8
	v_and_b32_e32 v61, 0xffff0000, v8
	v_pk_mul_f32 v[58:59], v[60:61], v[58:59]
	v_mov_b32_e32 v69, v55
	v_rcp_f32_e32 v57, v57
	v_rcp_f32_e32 v56, v56
	v_lshlrev_b32_e32 v60, 16, v43
	v_and_b32_e32 v61, 0xffff0000, v43
	v_pk_mul_f32 v[62:63], v[60:61], v[100:101] op_sel_hi:[1,0]
	v_exp_f32_e32 v62, v62
	v_exp_f32_e32 v63, v63
	v_pk_mul_f32 v[56:57], v[58:59], v[56:57]
	v_mov_b32_e32 v59, v54
	v_mov_b32_e32 v58, v56
	v_pk_mul_f32 v[58:59], v[58:59], v[58:59]
	v_mov_b32_e32 v68, v57
	v_pk_fma_f32 v[68:69], v[68:69], v[68:69], v[58:59]
	v_pk_add_f32 v[58:59], v[62:63], 1.0 op_sel_hi:[1,0]
	v_lshlrev_b32_e32 v62, 16, v23
	v_and_b32_e32 v63, 0xffff0000, v23
	v_pk_mul_f32 v[60:61], v[62:63], v[60:61]
	v_rcp_f32_e32 v59, v59
	v_lshlrev_b32_e32 v62, 16, v42
	v_and_b32_e32 v63, 0xffff0000, v42
	v_pk_mul_f32 v[70:71], v[62:63], v[100:101] op_sel_hi:[1,0]
	v_exp_f32_e32 v70, v70
	v_exp_f32_e32 v71, v71
	v_rcp_f32_e32 v58, v58
	s_nop 0
	v_pk_mul_f32 v[58:59], v[60:61], v[58:59]
	v_pk_add_f32 v[60:61], v[70:71], 1.0 op_sel_hi:[1,0]
	v_lshlrev_b32_e32 v70, 16, v22
	v_and_b32_e32 v71, 0xffff0000, v22
	v_pk_mul_f32 v[62:63], v[70:71], v[62:63]
	v_rcp_f32_e32 v61, v61
	v_rcp_f32_e32 v60, v60
	v_lshlrev_b32_e32 v70, 16, v41
	v_and_b32_e32 v71, 0xffff0000, v41
	v_pk_mul_f32 v[72:73], v[70:71], v[100:101] op_sel_hi:[1,0]
	v_exp_f32_e32 v72, v72
	v_exp_f32_e32 v73, v73
	v_pk_mul_f32 v[60:61], v[62:63], v[60:61]
	v_mov_b32_e32 v62, v58
	v_mov_b32_e32 v63, v60
	v_pk_add_f32 v[72:73], v[72:73], 1.0 op_sel_hi:[1,0]
	v_pk_mul_f32 v[62:63], v[62:63], v[62:63]
	v_mov_b32_e32 v74, v59
	v_mov_b32_e32 v75, v61
	v_pk_fma_f32 v[62:63], v[74:75], v[74:75], v[62:63]
	v_lshlrev_b32_e32 v74, 16, v21
	v_and_b32_e32 v75, 0xffff0000, v21
	v_pk_mul_f32 v[70:71], v[74:75], v[70:71]
	v_rcp_f32_e32 v73, v73
	v_lshlrev_b32_e32 v74, 16, v40
	v_and_b32_e32 v75, 0xffff0000, v40
	v_pk_mul_f32 v[84:85], v[74:75], v[100:101] op_sel_hi:[1,0]
	v_exp_f32_e32 v84, v84
	v_exp_f32_e32 v85, v85
	v_rcp_f32_e32 v72, v72
	s_nop 0
	v_pk_mul_f32 v[70:71], v[70:71], v[72:73]
	v_pk_add_f32 v[72:73], v[84:85], 1.0 op_sel_hi:[1,0]
	v_lshlrev_b32_e32 v84, 16, v20
	v_and_b32_e32 v85, 0xffff0000, v20
	v_pk_mul_f32 v[74:75], v[84:85], v[74:75]
	v_div_scale_f32 v86, s[6:7], v72, v72, 1.0
	v_rcp_f32_e32 v88, v86
	v_rcp_f32_e32 v73, v73
	s_mov_b32 s6, 0x3b000000
	v_fma_f32 v84, -v86, v88, 1.0
	v_fmac_f32_e32 v88, v84, v88
	v_div_scale_f32 v84, vcc, 1.0, v72, 1.0
	v_mul_f32_e32 v85, v84, v88
	v_fma_f32 v87, -v86, v85, v84
	v_fmac_f32_e32 v85, v87, v88
	v_fma_f32 v84, -v86, v85, v84
	v_div_fmas_f32 v84, v84, v88, v85
	v_div_fixup_f32 v72, v84, v72, 1.0
	v_pk_mul_f32 v[72:73], v[74:75], v[72:73]
	v_mov_b32_e32 v75, v70
	v_mov_b32_e32 v74, v72
	v_pk_mul_f32 v[74:75], v[74:75], v[74:75]
	v_mov_b32_e32 v84, v73
	v_mov_b32_e32 v85, v71
	v_pk_fma_f32 v[74:75], v[84:85], v[84:85], v[74:75]
	v_mov_b32_e32 v85, v68
	v_mov_b32_e32 v84, v74
	v_mov_b32_e32 v68, v75
	v_pk_add_f32 v[68:69], v[84:85], v[68:69]
	v_mov_b32_e32 v74, v63
	v_mov_b32_e32 v75, v53
	v_pk_add_f32 v[68:69], v[74:75], v[68:69]
	v_mov_b32_e32 v63, v52
	v_pk_add_f32 v[52:53], v[62:63], v[68:69]
	ds_bpermute_b32 v63, v65, v53
	ds_bpermute_b32 v62, v65, v52
	s_waitcnt lgkmcnt(0)
	v_pk_add_f32 v[52:53], v[52:53], v[62:63]
	ds_bpermute_b32 v63, v76, v53
	ds_bpermute_b32 v62, v76, v52
	s_waitcnt lgkmcnt(0)
	v_pk_add_f32 v[52:53], v[52:53], v[62:63]
	ds_bpermute_b32 v63, v77, v53
	ds_bpermute_b32 v62, v77, v52
	s_waitcnt lgkmcnt(0)
	v_pk_add_f32 v[52:53], v[52:53], v[62:63]
	ds_bpermute_b32 v63, v78, v53
	ds_bpermute_b32 v62, v78, v52
	s_waitcnt lgkmcnt(0)
	v_pk_add_f32 v[52:53], v[52:53], v[62:63]
	ds_bpermute_b32 v63, v79, v53
	ds_bpermute_b32 v62, v79, v52
	s_waitcnt lgkmcnt(0)
	v_pk_add_f32 v[52:53], v[52:53], v[62:63]
	ds_bpermute_b32 v63, v80, v53
	ds_bpermute_b32 v62, v80, v52
	s_waitcnt lgkmcnt(0)
; DI unsigned pk2(float lo, float hi) { const f32x2_t v = {lo, hi}; const bf16x2_t b = __builtin_convertvector(v, bf16x2_t); return __builtin_bit_cast(unsigned, b); }
; DI float lo16(unsigned w) { return __uint_as_float(w << 16); }
; DI float hi16(unsigned w) { return __uint_as_float(w & 0xffff0000u); }
; DI void gatenorm_pass(const Args& a, int G, const int tid) {
;     ...
;             for (int g = 0; g < 2; ++g) {
;                 float v[8]; float s = 0.f;
; #pragma unroll
;                 for (int e = 0; e < 4; ++e) { const float z0 = lo16(zw[q][g][e]), z1 = hi16(zw[q][g][e]); v[2 * e] = lo16(yw[q][g][e]) * z0 * __frcp_rn(1.0f + __expf(-z0)); v[2 * e + 1] = hi16(yw[q][g][e]) * z1 * __frcp_rn(1.0f + __expf(-z1)); s += v[2 * e] * v[2 * e] + v[2 * e + 1] * v[2 * e + 1]; }
;                 s = wave_sum(s); const float r = rsqrtf(s * (1.0f / 512.0f) + EPS);
;                 u32x4 w;
; #pragma unroll
;                 for (int e = 0; e < 4; ++e) w[e] = pk2(v[2 * e] * r, v[2 * e + 1] * r);
;                 *((u32x4*)(MIX + (size_t)m * LDMIX + 512 + g * 512) + lane) = w;
	v_pk_add_f32 v[52:53], v[52:53], v[62:63]
	v_pk_fma_f32 v[62:63], v[52:53], s[6:7], v[176:177] op_sel_hi:[1,0,0]
	v_mad_i64_i32 v[68:69], s[6:7], v83, s27, v[66:67]
	v_mul_f32_e32 v52, 0x4b800000, v63
	v_cmp_gt_f32_e32 vcc, s39, v63
	s_nop 1
	v_cndmask_b32_e32 v52, v63, v52, vcc
	v_rsq_f32_e32 v52, v52
	s_nop 0
	v_mul_f32_e32 v53, 0x45800000, v52
	v_cndmask_b32_e32 v74, v52, v53, vcc
	v_pk_mul_f32 v[52:53], v[56:57], v[74:75] op_sel_hi:[1,0]
	v_pk_mul_f32 v[54:55], v[54:55], v[74:75] op_sel_hi:[1,0]
	v_pk_mul_f32 v[50:51], v[50:51], v[74:75] op_sel_hi:[1,0]
	v_cvt_pk_bf16_f32 v52, v52, v53
	v_cvt_pk_bf16_f32 v53, v54, v55
	v_cvt_pk_bf16_f32 v54, v50, v51
	v_mul_f32_e32 v50, 0x4b800000, v62
	v_cmp_gt_f32_e32 vcc, s39, v62
	v_pk_mul_f32 v[48:49], v[48:49], v[74:75] op_sel_hi:[1,0]
	s_nop 0
	v_cndmask_b32_e32 v50, v62, v50, vcc
	v_rsq_f32_e32 v50, v50
	v_cvt_pk_bf16_f32 v55, v48, v49
	global_store_dwordx4 v[68:69], v[52:55], off offset:1024
	v_mul_f32_e32 v48, 0x45800000, v50
	s_nop 0
	v_cndmask_b32_e32 v52, v50, v48, vcc
	v_pk_mul_f32 v[48:49], v[72:73], v[52:53] op_sel_hi:[1,0]
	v_pk_mul_f32 v[50:51], v[70:71], v[52:53] op_sel_hi:[1,0]
	v_cvt_pk_bf16_f32 v48, v48, v49
	v_cvt_pk_bf16_f32 v49, v50, v51
	v_pk_mul_f32 v[50:51], v[60:61], v[52:53] op_sel_hi:[1,0]
	v_pk_mul_f32 v[52:53], v[58:59], v[52:53] op_sel_hi:[1,0]
	v_cvt_pk_bf16_f32 v50, v50, v51
	v_cvt_pk_bf16_f32 v51, v52, v53
	global_store_dwordx4 v[68:69], v[48:51], off offset:2048
	s_or_b64 exec, exec, s[4:5]
	s_and_saveexec_b64 s[4:5], s[40:41]
	s_cbranch_execz .LBB0_96
.LBB0_108:
	v_lshlrev_b32_e32 v48, 16, v31
	v_and_b32_e32 v49, 0xffff0000, v31
	v_pk_mul_f32 v[50:51], v[48:49], v[100:101] op_sel_hi:[1,0]
	v_exp_f32_e32 v50, v50
	v_exp_f32_e32 v51, v51
	v_lshlrev_b32_e32 v52, 16, v3
	v_and_b32_e32 v53, 0xffff0000, v3
	v_pk_mul_f32 v[48:49], v[52:53], v[48:49]
	v_pk_add_f32 v[50:51], v[50:51], 1.0 op_sel_hi:[1,0]
	v_rcp_f32_e32 v51, v51
	v_lshlrev_b32_e32 v52, 16, v30
	v_and_b32_e32 v53, 0xffff0000, v30
	v_pk_mul_f32 v[54:55], v[52:53], v[100:101] op_sel_hi:[1,0]
	v_exp_f32_e32 v54, v54
	v_exp_f32_e32 v55, v55
	v_rcp_f32_e32 v50, v50
	s_nop 0
	v_pk_mul_f32 v[48:49], v[48:49], v[50:51]
	v_pk_add_f32 v[50:51], v[54:55], 1.0 op_sel_hi:[1,0]
	v_lshlrev_b32_e32 v54, 16, v2
	v_and_b32_e32 v55, 0xffff0000, v2
	v_pk_mul_f32 v[52:53], v[54:55], v[52:53]
	v_rcp_f32_e32 v51, v51
	v_rcp_f32_e32 v50, v50
	v_lshlrev_b32_e32 v54, 16, v29
	v_and_b32_e32 v55, 0xffff0000, v29
	v_pk_mul_f32 v[56:57], v[54:55], v[100:101] op_sel_hi:[1,0]
	v_exp_f32_e32 v56, v56
	v_exp_f32_e32 v57, v57
	v_pk_mul_f32 v[50:51], v[52:53], v[50:51]
	v_mov_b32_e32 v52, v48
	v_mov_b32_e32 v53, v50
	v_pk_add_f32 v[56:57], v[56:57], 1.0 op_sel_hi:[1,0]
	v_pk_mul_f32 v[52:53], v[52:53], v[52:53]
	v_mov_b32_e32 v58, v49
	v_mov_b32_e32 v59, v51
	v_pk_fma_f32 v[52:53], v[58:59], v[58:59], v[52:53]
	v_lshlrev_b32_e32 v58, 16, v1
	v_and_b32_e32 v59, 0xffff0000, v1
	v_pk_mul_f32 v[54:55], v[58:59], v[54:55]
	v_rcp_f32_e32 v57, v57
	v_lshlrev_b32_e32 v58, 16, v28
	v_and_b32_e32 v59, 0xffff0000, v28
	v_pk_mul_f32 v[60:61], v[58:59], v[100:101] op_sel_hi:[1,0]
	v_exp_f32_e32 v60, v60
	v_exp_f32_e32 v61, v61
	v_rcp_f32_e32 v56, v56
	s_nop 0
	v_pk_mul_f32 v[54:55], v[54:55], v[56:57]
	v_pk_add_f32 v[56:57], v[60:61], 1.0 op_sel_hi:[1,0]
	v_lshlrev_b32_e32 v60, 16, v0
	v_and_b32_e32 v61, 0xffff0000, v0
	v_pk_mul_f32 v[58:59], v[60:61], v[58:59]
	v_mov_b32_e32 v69, v55
	v_rcp_f32_e32 v57, v57
	v_rcp_f32_e32 v56, v56
	v_lshlrev_b32_e32 v60, 16, v27
	v_and_b32_e32 v61, 0xffff0000, v27
	v_pk_mul_f32 v[62:63], v[60:61], v[100:101] op_sel_hi:[1,0]
	v_exp_f32_e32 v62, v62
	v_exp_f32_e32 v63, v63
	v_pk_mul_f32 v[56:57], v[58:59], v[56:57]
	v_mov_b32_e32 v59, v54
	v_mov_b32_e32 v58, v56
	v_pk_mul_f32 v[58:59], v[58:59], v[58:59]
	v_mov_b32_e32 v68, v57
	v_pk_fma_f32 v[68:69], v[68:69], v[68:69], v[58:59]
	v_pk_add_f32 v[58:59], v[62:63], 1.0 op_sel_hi:[1,0]
	v_lshlrev_b32_e32 v62, 16, v15
	v_and_b32_e32 v63, 0xffff0000, v15
	v_pk_mul_f32 v[60:61], v[62:63], v[60:61]
	v_rcp_f32_e32 v59, v59
	v_lshlrev_b32_e32 v62, 16, v26
	v_and_b32_e32 v63, 0xffff0000, v26
	v_pk_mul_f32 v[70:71], v[62:63], v[100:101] op_sel_hi:[1,0]
	v_exp_f32_e32 v70, v70
	v_exp_f32_e32 v71, v71
	v_rcp_f32_e32 v58, v58
	s_nop 0
	v_pk_mul_f32 v[58:59], v[60:61], v[58:59]
	v_pk_add_f32 v[60:61], v[70:71], 1.0 op_sel_hi:[1,0]
	v_lshlrev_b32_e32 v70, 16, v14
	v_and_b32_e32 v71, 0xffff0000, v14
	v_pk_mul_f32 v[62:63], v[70:71], v[62:63]
	v_rcp_f32_e32 v61, v61
	v_rcp_f32_e32 v60, v60
	v_lshlrev_b32_e32 v70, 16, v25
	v_and_b32_e32 v71, 0xffff0000, v25
	v_pk_mul_f32 v[72:73], v[70:71], v[100:101] op_sel_hi:[1,0]
	v_exp_f32_e32 v72, v72
	v_exp_f32_e32 v73, v73
	v_pk_mul_f32 v[60:61], v[62:63], v[60:61]
	v_mov_b32_e32 v62, v58
	v_mov_b32_e32 v63, v60
	v_pk_add_f32 v[72:73], v[72:73], 1.0 op_sel_hi:[1,0]
	v_pk_mul_f32 v[62:63], v[62:63], v[62:63]
	v_mov_b32_e32 v74, v59
	v_mov_b32_e32 v75, v61
	v_pk_fma_f32 v[62:63], v[74:75], v[74:75], v[62:63]
	v_lshlrev_b32_e32 v74, 16, v13
	v_and_b32_e32 v75, 0xffff0000, v13
	v_pk_mul_f32 v[70:71], v[74:75], v[70:71]
	v_rcp_f32_e32 v73, v73
	v_lshlrev_b32_e32 v74, 16, v24
	v_and_b32_e32 v75, 0xffff0000, v24
	v_pk_mul_f32 v[84:85], v[74:75], v[100:101] op_sel_hi:[1,0]
	v_exp_f32_e32 v84, v84
	v_exp_f32_e32 v85, v85
	v_rcp_f32_e32 v72, v72
	s_nop 0
	v_pk_mul_f32 v[70:71], v[70:71], v[72:73]
	v_pk_add_f32 v[72:73], v[84:85], 1.0 op_sel_hi:[1,0]
	v_lshlrev_b32_e32 v84, 16, v12
	v_and_b32_e32 v85, 0xffff0000, v12
	v_pk_mul_f32 v[74:75], v[84:85], v[74:75]
	v_div_scale_f32 v84, s[6:7], v72, v72, 1.0
	v_rcp_f32_e32 v87, v84
	v_rcp_f32_e32 v73, v73
	s_mov_b32 s6, 0x3b000000
	v_fma_f32 v83, -v84, v87, 1.0
	v_fmac_f32_e32 v87, v83, v87
	v_div_scale_f32 v83, vcc, 1.0, v72, 1.0
	v_mul_f32_e32 v85, v83, v87
	v_fma_f32 v86, -v84, v85, v83
	v_fmac_f32_e32 v85, v86, v87
	v_fma_f32 v83, -v84, v85, v83
	v_div_fmas_f32 v83, v83, v87, v85
	v_div_fixup_f32 v72, v83, v72, 1.0
	v_pk_mul_f32 v[72:73], v[74:75], v[72:73]
	v_mov_b32_e32 v75, v70
	v_mov_b32_e32 v74, v72
	v_pk_mul_f32 v[74:75], v[74:75], v[74:75]
	v_mov_b32_e32 v84, v73
	v_mov_b32_e32 v85, v71
	v_pk_fma_f32 v[74:75], v[84:85], v[84:85], v[74:75]
	v_mov_b32_e32 v85, v68
	v_mov_b32_e32 v84, v74
	v_mov_b32_e32 v68, v75
	v_pk_add_f32 v[68:69], v[84:85], v[68:69]
	v_mov_b32_e32 v74, v63
	v_mov_b32_e32 v75, v53
	v_pk_add_f32 v[68:69], v[74:75], v[68:69]
	v_mov_b32_e32 v63, v52
	v_pk_add_f32 v[52:53], v[62:63], v[68:69]
	ds_bpermute_b32 v63, v65, v53
	ds_bpermute_b32 v62, v65, v52
	s_waitcnt lgkmcnt(0)
; DI unsigned pk2(float lo, float hi) { const f32x2_t v = {lo, hi}; const bf16x2_t b = __builtin_convertvector(v, bf16x2_t); return __builtin_bit_cast(unsigned, b); }
; DI void gatenorm_pass(const Args& a, int G, const int tid) {
;     ...
;                 s = wave_sum(s); const float r = rsqrtf(s * (1.0f / 512.0f) + EPS);
;                 u32x4 w;
; #pragma unroll
;                 for (int e = 0; e < 4; ++e) w[e] = pk2(v[2 * e] * r, v[2 * e + 1] * r);
;                 *((u32x4*)(MIX + (size_t)m * LDMIX + 512 + g * 512) + lane) = w;
	v_pk_add_f32 v[52:53], v[52:53], v[62:63]
	ds_bpermute_b32 v63, v76, v53
	ds_bpermute_b32 v62, v76, v52
	s_waitcnt lgkmcnt(0)
	v_pk_add_f32 v[52:53], v[52:53], v[62:63]
	ds_bpermute_b32 v63, v77, v53
	ds_bpermute_b32 v62, v77, v52
	s_waitcnt lgkmcnt(0)
	v_pk_add_f32 v[52:53], v[52:53], v[62:63]
	ds_bpermute_b32 v63, v78, v53
	ds_bpermute_b32 v62, v78, v52
	s_waitcnt lgkmcnt(0)
	v_pk_add_f32 v[52:53], v[52:53], v[62:63]
	ds_bpermute_b32 v63, v79, v53
	ds_bpermute_b32 v62, v79, v52
	s_waitcnt lgkmcnt(0)
	v_pk_add_f32 v[52:53], v[52:53], v[62:63]
	ds_bpermute_b32 v63, v80, v53
	ds_bpermute_b32 v62, v80, v52
	s_waitcnt lgkmcnt(0)
	v_pk_add_f32 v[52:53], v[52:53], v[62:63]
	v_pk_fma_f32 v[62:63], v[52:53], s[6:7], v[176:177] op_sel_hi:[1,0,0]
	v_mad_i64_i32 v[68:69], s[6:7], v82, s27, v[66:67]
	v_mul_f32_e32 v52, 0x4b800000, v63
	v_cmp_gt_f32_e32 vcc, s39, v63
	s_nop 1
	v_cndmask_b32_e32 v52, v63, v52, vcc
	v_rsq_f32_e32 v52, v52
	s_nop 0
	v_mul_f32_e32 v53, 0x45800000, v52
	v_cndmask_b32_e32 v74, v52, v53, vcc
	v_pk_mul_f32 v[52:53], v[56:57], v[74:75] op_sel_hi:[1,0]
	v_pk_mul_f32 v[54:55], v[54:55], v[74:75] op_sel_hi:[1,0]
	v_pk_mul_f32 v[50:51], v[50:51], v[74:75] op_sel_hi:[1,0]
	v_cvt_pk_bf16_f32 v52, v52, v53
	v_cvt_pk_bf16_f32 v53, v54, v55
	v_cvt_pk_bf16_f32 v54, v50, v51
	v_mul_f32_e32 v50, 0x4b800000, v62
	v_cmp_gt_f32_e32 vcc, s39, v62
	v_pk_mul_f32 v[48:49], v[48:49], v[74:75] op_sel_hi:[1,0]
	s_nop 0
	v_cndmask_b32_e32 v50, v62, v50, vcc
	v_rsq_f32_e32 v50, v50
	v_cvt_pk_bf16_f32 v55, v48, v49
	global_store_dwordx4 v[68:69], v[52:55], off offset:1024
	v_mul_f32_e32 v48, 0x45800000, v50
	s_nop 0
	v_cndmask_b32_e32 v52, v50, v48, vcc
	v_pk_mul_f32 v[48:49], v[72:73], v[52:53] op_sel_hi:[1,0]
	v_pk_mul_f32 v[50:51], v[70:71], v[52:53] op_sel_hi:[1,0]
	v_cvt_pk_bf16_f32 v48, v48, v49
	v_cvt_pk_bf16_f32 v49, v50, v51
	v_pk_mul_f32 v[50:51], v[60:61], v[52:53] op_sel_hi:[1,0]
	v_pk_mul_f32 v[52:53], v[58:59], v[52:53] op_sel_hi:[1,0]
	v_cvt_pk_bf16_f32 v50, v50, v51
	v_cvt_pk_bf16_f32 v51, v52, v53
	global_store_dwordx4 v[68:69], v[48:51], off offset:2048
	s_branch .LBB0_96
